# P0: the 64 SSM-operator workgroups take no RMSNorm rows; the other 192 cover all 16384 rows
# baseline (speedup 1.0000x reference)
; __device__ __forceinline__ unsigned cvt_pk_bf16(float lo, float hi) { unsigned r; asm volatile("v_cvt_pk_bf16_f32 %0, %1, %2" : "=v"(r) : "v"(lo), "v"(hi)); return r; }
; __global__ void __launch_bounds__(NWAVES * 64, 2) hymba_fwd(Args a) {
;     ...
;         const bool isS = bx < NG;
;         const int NW2 = isS ? NG * NWAVES : (G - NG) * NWAVES, mEnd = isS ? 1024 : M;
;         for (int m = isS ? bx * NWAVES + wave : 1024 + (bx - NG) * NWAVES + wave; m < mEnd; m += 2 * NW2) {
;             f32x4 v[2][8]; float s[2];
; #pragma unroll
;             for (int q = 0; q < 2; ++q) { const int mq = (m + q * NW2 < mEnd) ? m + q * NW2 : m; const f32x4* xr = (const f32x4*)(a.x + (size_t)mq * DM);
; #pragma unroll
;                 for (int j = 0; j < 4; ++j) { v[q][2 * j] = xr[128 * j + 2 * lane]; v[q][2 * j + 1] = xr[128 * j + 2 * lane + 1]; } }
; #pragma unroll
;             for (int q = 0; q < 2; ++q) { float t = 0.f;
; #pragma unroll
;                 for (int j = 0; j < 8; ++j) t += (v[q][j].x * v[q][j].x + v[q][j].y * v[q][j].y) + (v[q][j].z * v[q][j].z + v[q][j].w * v[q][j].w);
;                 s[q] = t; }
; #pragma unroll
;             for (int q = 0; q < 2; ++q) { const int mm = m + q * NW2; if (mm >= mEnd) continue;
;                 const float ms = wave_sum(s[q]) * (1.0f / DM) + RMS_EPS; const float r = 1.0f / sqrtf(ms);
;                 if (lane == 0) ((float*)(ws + WS_RX))[mm] = sqrtf(ms);
;                 v4u* o = (v4u*)(R1 + (size_t)mm * DM);
; #pragma unroll
;                 for (int j = 0; j < 4; ++j) { v4u w; w.x = cvt_pk_bf16(v[q][2 * j].x * r, v[q][2 * j].y * r); w.y = cvt_pk_bf16(v[q][2 * j].z * r, v[q][2 * j].w * r);
;                     w.z = cvt_pk_bf16(v[q][2 * j + 1].x * r, v[q][2 * j + 1].y * r); w.w = cvt_pk_bf16(v[q][2 * j + 1].z * r, v[q][2 * j + 1].w * r); o[64 * j + lane] = w; } }
;         }
.LBB0_331:
	s_add_u32 s60, s94, 0x7000000
	s_load_dwordx16 s[36:51], s[0:1], 0x80
	s_addc_u32 s61, s95, 0
	s_add_i32 s4, s18, 0xfffffe00
	s_and_b64 s[0:1], s[14:15], exec
	s_cselect_b32 s0, s18, s4
	s_add_i32 s8, s19, s0
	s_and_b64 s[0:1], s[14:15], exec
	s_cselect_b32 s8, s16, s8
	s_cmp_ge_i32 s8, s16
	v_mbcnt_lo_u32_b32 v1, -1, 0
	s_cbranch_scc1 .LBB0_340
	s_waitcnt vmcnt(0)
	v_mbcnt_hi_u32_b32 v3, -1, v1
	v_and_b32_e32 v5, 64, v3
	v_add_u32_e32 v5, 64, v5
	v_xor_b32_e32 v7, 1, v3
	v_cmp_lt_i32_e32 vcc, v7, v5
	v_lshlrev_b32_e32 v2, 1, v32
	s_add_u32 s4, s94, 0x6e00000
	v_cndmask_b32_e32 v7, v3, v7, vcc
	v_lshlrev_b32_e32 v70, 2, v7
	v_xor_b32_e32 v7, 2, v3
	v_cmp_lt_i32_e32 vcc, v7, v5
	v_mov_b32_e32 v67, 0
	v_or_b32_e32 v4, 0x100, v2
	v_cndmask_b32_e32 v7, v3, v7, vcc
	v_lshlrev_b32_e32 v71, 2, v7
	v_xor_b32_e32 v7, 4, v3
	v_cmp_lt_i32_e32 vcc, v7, v5
	v_or_b32_e32 v6, 0x180, v2
	v_lshlrev_b32_e32 v66, 4, v32
	v_cndmask_b32_e32 v7, v3, v7, vcc
	v_lshlrev_b32_e32 v72, 2, v7
	v_xor_b32_e32 v7, 8, v3
	v_cmp_lt_i32_e32 vcc, v7, v5
	v_cmp_eq_u32_e64 s[0:1], 0, v32
	s_addc_u32 s5, s95, 0
	v_cndmask_b32_e32 v7, v3, v7, vcc
	v_lshlrev_b32_e32 v73, 2, v7
	v_xor_b32_e32 v7, 16, v3
	v_cmp_lt_i32_e32 vcc, v7, v5
	v_lshl_add_u64 v[68:69], s[60:61], 0, v[66:67]
	s_lshl_b32 s17, s3, 1
	v_cndmask_b32_e32 v7, v3, v7, vcc
	v_lshlrev_b32_e32 v74, 2, v7
	v_xor_b32_e32 v7, 32, v3
	v_cmp_lt_i32_e32 vcc, v7, v5
	v_lshlrev_b32_e32 v66, 4, v2
	v_lshlrev_b32_e32 v76, 4, v4
	v_cndmask_b32_e32 v3, v3, v7, vcc
	v_lshlrev_b32_e32 v75, 2, v3
	v_lshlrev_b32_e32 v77, 4, v6
	v_mov_b32_e32 v78, 0x358637bd
	s_mov_b32 s18, 0xf800000
	v_mov_b32_e32 v79, 0x260
	s_branch .LBB0_335
